# barrier spin loops poll without s_sleep (s_nop instead)
# baseline (speedup 1.0000x reference)
.LBB0_14:
	s_nop 0
	global_load_dword v2, v0, s[6:7] offset:32 sc1
	s_waitcnt vmcnt(0)
	v_and_b32_e32 v2, 0xffff0000, v2
	v_cmp_ne_u32_e32 vcc, v2, v1
	s_or_b64 s[8:9], vcc, s[8:9]
	s_andn2_b64 exec, exec, s[8:9]
	s_cbranch_execnz .LBB0_14

.LBB0_53:
	global_load_dword v15, v16, s[10:11] sc1
	s_waitcnt lgkmcnt(0)
	global_load_dword v0, v16, s[12:13] sc1
	global_load_dword v1, v16, s[14:15] sc1
	global_load_dword v2, v16, s[16:17] sc1
	global_load_dword v3, v16, s[18:19] sc1
	global_load_dword v4, v16, s[20:21] sc1
	global_load_dword v5, v16, s[22:23] sc1
	global_load_dword v6, v16, s[24:25] sc1
	global_load_dword v7, v16, s[26:27] sc1
	global_load_dword v8, v16, s[28:29] sc1
	global_load_dword v9, v16, s[30:31] sc1
	global_load_dword v10, v16, s[34:35] sc1
	global_load_dword v11, v16, s[36:37] sc1
	global_load_dword v12, v16, s[42:43] sc1
	global_load_dword v13, v16, s[44:45] sc1
	global_load_dword v14, v16, s[46:47] sc1
	s_mov_b64 s[48:49], -1
	s_mov_b64 s[50:51], -1
	s_waitcnt vmcnt(14)
	v_add_u32_e32 v17, v0, v15
	s_waitcnt vmcnt(13)
	v_add_u32_e32 v17, v17, v1
	s_waitcnt vmcnt(12)
	v_add_u32_e32 v17, v17, v2
	s_waitcnt vmcnt(11)
	v_add_u32_e32 v17, v17, v3
	s_waitcnt vmcnt(10)
	v_add_u32_e32 v17, v17, v4
	s_waitcnt vmcnt(9)
	v_add_u32_e32 v17, v17, v5
	s_waitcnt vmcnt(8)
	v_add_u32_e32 v17, v17, v6
	s_waitcnt vmcnt(7)
	v_add_u32_e32 v17, v17, v7
	s_waitcnt vmcnt(6)
	v_add_u32_e32 v17, v17, v8
	s_waitcnt vmcnt(5)
	v_add_u32_e32 v17, v17, v9
	s_waitcnt vmcnt(4)
	v_add_u32_e32 v17, v17, v10
	s_waitcnt vmcnt(3)
	v_add_u32_e32 v17, v17, v11
	s_waitcnt vmcnt(2)
	v_add_u32_e32 v17, v17, v12
	s_waitcnt vmcnt(1)
	v_add_u32_e32 v17, v17, v13
	s_waitcnt vmcnt(0)
	v_add_u32_e32 v17, v17, v14
	v_cmp_eq_u32_e32 vcc, s33, v17
	s_cbranch_vccnz .LBB0_52
	s_and_b32 s41, s39, 0xff
	s_cmp_eq_u32 s41, 0
	s_mov_b64 s[52:53], -1
	s_nop 0
	s_cbranch_scc1 .LBB0_57
	s_and_b64 vcc, exec, s[52:53]
	s_cbranch_vccz .LBB0_52

.LBB0_71:
	s_and_b32 s24, s3, 0xff
	s_mov_b64 s[22:23], -1
	s_cmp_lg_u32 s24, 0
	s_mov_b64 s[26:27], -1
	s_nop 0
	s_cbranch_scc0 .LBB0_74
	s_and_b64 vcc, exec, s[26:27]
	s_cbranch_vccz .LBB0_70

.LBB0_88:
	s_and_b32 s20, s3, 0xff
	s_cmp_lg_u32 s20, 0
	s_mov_b64 s[22:23], -1
	s_nop 0
	s_cbranch_scc0 .LBB0_91
	s_mov_b64 s[24:25], -1
	s_and_b64 vcc, exec, s[22:23]
	s_cbranch_vccz .LBB0_87

.LBB0_216:
	global_load_dword v15, v145, s[6:7] sc1
	s_waitcnt lgkmcnt(0)
	global_load_dword v0, v145, s[8:9] sc1
	global_load_dword v1, v145, s[10:11] sc1
	global_load_dword v2, v145, s[12:13] sc1
	global_load_dword v3, v145, s[14:15] sc1
	global_load_dword v4, v145, s[16:17] sc1
	global_load_dword v5, v145, s[18:19] sc1
	global_load_dword v6, v145, s[24:25] sc1
	global_load_dword v7, v145, s[26:27] sc1
	global_load_dword v8, v145, s[28:29] sc1
	global_load_dword v9, v145, s[30:31] sc1
	global_load_dword v10, v145, s[34:35] sc1
	global_load_dword v11, v145, s[36:37] sc1
	global_load_dword v12, v145, s[50:51] sc1
	global_load_dword v13, v145, s[52:53] sc1
	global_load_dword v14, v145, s[54:55] sc1
	s_mov_b64 s[56:57], -1
	s_mov_b64 s[66:67], -1
	s_waitcnt vmcnt(14)
	v_add_u32_e32 v16, v0, v15
	s_waitcnt vmcnt(13)
	v_add_u32_e32 v16, v16, v1
	s_waitcnt vmcnt(12)
	v_add_u32_e32 v16, v16, v2
	s_waitcnt vmcnt(11)
	v_add_u32_e32 v16, v16, v3
	s_waitcnt vmcnt(10)
	v_add_u32_e32 v16, v16, v4
	s_waitcnt vmcnt(9)
	v_add_u32_e32 v16, v16, v5
	s_waitcnt vmcnt(8)
	v_add_u32_e32 v16, v16, v6
	s_waitcnt vmcnt(7)
	v_add_u32_e32 v16, v16, v7
	s_waitcnt vmcnt(6)
	v_add_u32_e32 v16, v16, v8
	s_waitcnt vmcnt(5)
	v_add_u32_e32 v16, v16, v9
	s_waitcnt vmcnt(4)
	v_add_u32_e32 v16, v16, v10
	s_waitcnt vmcnt(3)
	v_add_u32_e32 v16, v16, v11
	s_waitcnt vmcnt(2)
	v_add_u32_e32 v16, v16, v12
	s_waitcnt vmcnt(1)
	v_add_u32_e32 v16, v16, v13
	s_waitcnt vmcnt(0)
	v_add_u32_e32 v16, v16, v14
	v_cmp_eq_u32_e32 vcc, s33, v16
	s_cbranch_vccnz .LBB0_215
	s_and_b32 s56, s73, 0xff
	s_cmp_eq_u32 s56, 0
	s_mov_b64 s[56:57], -1
	s_mov_b64 s[70:71], -1
	s_nop 0
	s_cbranch_scc1 .LBB0_220
	s_and_b64 vcc, exec, s[70:71]
	s_cbranch_vccz .LBB0_215

.LBB0_234:
	s_and_b32 s24, s28, 0xff
	s_mov_b64 s[18:19], -1
	s_cmp_lg_u32 s24, 0
	s_mov_b64 s[26:27], -1
	s_nop 0
	s_cbranch_scc0 .LBB0_237
	s_and_b64 vcc, exec, s[26:27]
	s_cbranch_vccz .LBB0_233

.LBB0_282:
	global_load_dword v15, v145, s[10:11] sc1
	s_waitcnt lgkmcnt(0)
	global_load_dword v0, v145, s[12:13] sc1
	global_load_dword v1, v145, s[14:15] sc1
	global_load_dword v2, v145, s[16:17] sc1
	global_load_dword v3, v145, s[18:19] sc1
	global_load_dword v4, v145, s[24:25] sc1
	global_load_dword v5, v145, s[26:27] sc1
	global_load_dword v6, v145, s[28:29] sc1
	global_load_dword v7, v145, s[30:31] sc1
	global_load_dword v8, v145, s[34:35] sc1
	global_load_dword v9, v145, s[36:37] sc1
	global_load_dword v10, v145, s[50:51] sc1
	global_load_dword v11, v145, s[52:53] sc1
	global_load_dword v12, v145, s[54:55] sc1
	global_load_dword v13, v145, s[56:57] sc1
	global_load_dword v14, v145, s[66:67] sc1
	s_mov_b64 s[70:71], -1
	s_mov_b64 s[72:73], -1
	s_waitcnt vmcnt(14)
	v_add_u32_e32 v16, v0, v15
	s_waitcnt vmcnt(13)
	v_add_u32_e32 v16, v16, v1
	s_waitcnt vmcnt(12)
	v_add_u32_e32 v16, v16, v2
	s_waitcnt vmcnt(11)
	v_add_u32_e32 v16, v16, v3
	s_waitcnt vmcnt(10)
	v_add_u32_e32 v16, v16, v4
	s_waitcnt vmcnt(9)
	v_add_u32_e32 v16, v16, v5
	s_waitcnt vmcnt(8)
	v_add_u32_e32 v16, v16, v6
	s_waitcnt vmcnt(7)
	v_add_u32_e32 v16, v16, v7
	s_waitcnt vmcnt(6)
	v_add_u32_e32 v16, v16, v8
	s_waitcnt vmcnt(5)
	v_add_u32_e32 v16, v16, v9
	s_waitcnt vmcnt(4)
	v_add_u32_e32 v16, v16, v10
	s_waitcnt vmcnt(3)
	v_add_u32_e32 v16, v16, v11
	s_waitcnt vmcnt(2)
	v_add_u32_e32 v16, v16, v12
	s_waitcnt vmcnt(1)
	v_add_u32_e32 v16, v16, v13
	s_waitcnt vmcnt(0)
	v_add_u32_e32 v16, v16, v14
	v_cmp_eq_u32_e32 vcc, s33, v16
	s_cbranch_vccnz .LBB0_281
	s_and_b32 s70, s82, 0xff
	s_cmp_eq_u32 s70, 0
	s_mov_b64 s[70:71], -1
	s_mov_b64 s[74:75], -1
	s_nop 0
	s_cbranch_scc1 .LBB0_286
	s_and_b64 vcc, exec, s[74:75]
	s_cbranch_vccz .LBB0_281

.LBB0_300:
	s_and_b32 s28, s34, 0xff
	s_mov_b64 s[26:27], -1
	s_cmp_lg_u32 s28, 0
	s_mov_b64 s[30:31], -1
	s_nop 0
	s_cbranch_scc0 .LBB0_303
	s_and_b64 vcc, exec, s[30:31]
	s_cbranch_vccz .LBB0_299

.LBB0_317:
	s_and_b32 s26, s30, 0xff
	s_mov_b64 s[24:25], -1
	s_cmp_lg_u32 s26, 0
	s_mov_b64 s[28:29], -1
	s_nop 0
	s_cbranch_scc0 .LBB0_320
	s_and_b64 vcc, exec, s[28:29]
	s_cbranch_vccz .LBB0_316

.LBB0_446:
	s_and_b32 s22, s26, 0xff
	s_mov_b64 s[18:19], -1
	s_cmp_lg_u32 s22, 0
	s_mov_b64 s[24:25], -1
	s_nop 0
	s_cbranch_scc0 .LBB0_449
	s_and_b64 vcc, exec, s[24:25]
	s_cbranch_vccz .LBB0_445

.LBB0_644:
	global_load_dword v51, v[4:5], off sc1
	global_load_dword v49, v[6:7], off sc1
	global_load_dword v50, v[8:9], off sc1
	global_load_dword v47, v[10:11], off sc1
	global_load_dword v48, v[12:13], off sc1
	global_load_dword v45, v[14:15], off sc1
	global_load_dword v46, v[16:17], off sc1
	global_load_dword v43, v[18:19], off sc1
	global_load_dword v44, v[20:21], off sc1
	global_load_dword v41, v[22:23], off sc1
	global_load_dword v42, v[24:25], off sc1
	global_load_dword v39, v[26:27], off sc1
	global_load_dword v40, v[28:29], off sc1
	global_load_dword v37, v[30:31], off sc1
	global_load_dword v38, v[32:33], off sc1
	global_load_dword v36, v[34:35], off sc1
	s_or_b64 s[12:13], s[12:13], exec
	s_or_b64 s[8:9], s[8:9], exec
	s_waitcnt vmcnt(14)
	v_add_u32_e32 v52, v49, v51
	s_waitcnt vmcnt(12)
	v_add3_u32 v52, v52, v50, v47
	s_waitcnt vmcnt(10)
	v_add3_u32 v52, v52, v48, v45
	s_waitcnt vmcnt(8)
	v_add3_u32 v52, v52, v46, v43
	s_waitcnt vmcnt(6)
	v_add3_u32 v52, v52, v44, v41
	s_waitcnt vmcnt(4)
	v_add3_u32 v52, v52, v42, v39
	s_waitcnt vmcnt(2)
	v_add3_u32 v52, v52, v40, v37
	s_waitcnt vmcnt(0)
	v_add3_u32 v52, v52, v38, v36
	v_cmp_ne_u32_e32 vcc, s33, v52
	s_and_saveexec_b64 s[14:15], vcc
	s_cbranch_execz .LBB0_643
	s_and_b32 s18, s24, 0xff
	s_mov_b64 s[16:17], -1
	s_cmp_eq_u32 s18, 0
	s_mov_b64 s[20:21], -1
	s_mov_b64 s[18:19], -1
	s_nop 0
	s_cbranch_scc1 .LBB0_647
	s_and_saveexec_b64 s[22:23], s[20:21]
	s_cbranch_execz .LBB0_642
	s_branch .LBB0_650

.LBB0_658:
	s_and_b32 s18, s24, 0xff
	s_mov_b64 s[16:17], -1
	s_cmp_lg_u32 s18, 0
	s_mov_b64 s[18:19], -1
	s_nop 0
	s_cbranch_scc1 .LBB0_662
	global_load_dword v4, v[0:1], off sc1
	s_mov_b64 s[18:19], 0
	s_mov_b64 s[20:21], -1
	s_waitcnt vmcnt(0)
	v_cmp_eq_u32_e32 vcc, 0, v4
	s_and_saveexec_b64 s[22:23], vcc
	s_cmp_lt_u32 s24, 0x40001
	s_cselect_b64 s[18:19], -1, 0
	s_xor_b64 s[20:21], exec, -1
	s_and_b64 s[18:19], s[18:19], exec
	s_or_b64 exec, exec, s[22:23]

.LBB0_672:
	s_and_b32 s16, s22, 0xff
	s_mov_b64 s[14:15], -1
	s_cmp_lg_u32 s16, 0
	s_mov_b64 s[18:19], -1
	s_nop 0
	s_cbranch_scc0 .LBB0_674
	s_and_saveexec_b64 s[20:21], s[18:19]
	s_cbranch_execz .LBB0_671
	s_branch .LBB0_677

.LBB0_709:
	global_load_dword v15, v145, s[8:9] sc1
	s_waitcnt lgkmcnt(0)
	global_load_dword v0, v145, s[10:11] sc1
	global_load_dword v1, v145, s[20:21] sc1
	global_load_dword v2, v145, s[26:27] sc1
	global_load_dword v3, v145, s[28:29] sc1
	global_load_dword v4, v145, s[30:31] sc1
	global_load_dword v5, v145, s[34:35] sc1
	global_load_dword v6, v145, s[36:37] sc1
	global_load_dword v7, v145, s[50:51] sc1
	global_load_dword v8, v145, s[52:53] sc1
	global_load_dword v9, v145, s[54:55] sc1
	global_load_dword v10, v145, s[56:57] sc1
	global_load_dword v11, v145, s[66:67] sc1
	global_load_dword v12, v145, s[70:71] sc1
	global_load_dword v13, v145, s[72:73] sc1
	global_load_dword v14, v145, s[74:75] sc1
	s_mov_b64 s[82:83], -1
	s_mov_b64 s[88:89], -1
	s_waitcnt vmcnt(14)
	v_add_u32_e32 v16, v0, v15
	s_waitcnt vmcnt(13)
	v_add_u32_e32 v16, v16, v1
	s_waitcnt vmcnt(12)
	v_add_u32_e32 v16, v16, v2
	s_waitcnt vmcnt(11)
	v_add_u32_e32 v16, v16, v3
	s_waitcnt vmcnt(10)
	v_add_u32_e32 v16, v16, v4
	s_waitcnt vmcnt(9)
	v_add_u32_e32 v16, v16, v5
	s_waitcnt vmcnt(8)
	v_add_u32_e32 v16, v16, v6
	s_waitcnt vmcnt(7)
	v_add_u32_e32 v16, v16, v7
	s_waitcnt vmcnt(6)
	v_add_u32_e32 v16, v16, v8
	s_waitcnt vmcnt(5)
	v_add_u32_e32 v16, v16, v9
	s_waitcnt vmcnt(4)
	v_add_u32_e32 v16, v16, v10
	s_waitcnt vmcnt(3)
	v_add_u32_e32 v16, v16, v11
	s_waitcnt vmcnt(2)
	v_add_u32_e32 v16, v16, v12
	s_waitcnt vmcnt(1)
	v_add_u32_e32 v16, v16, v13
	s_waitcnt vmcnt(0)
	v_add_u32_e32 v16, v16, v14
	v_cmp_eq_u32_e32 vcc, s33, v16
	s_cbranch_vccnz .LBB0_708
	s_and_b32 s18, s13, 0xff
	s_cmp_eq_u32 s18, 0
	s_mov_b64 s[94:95], -1
	s_nop 0
	s_cbranch_scc1 .LBB0_713
	s_and_b64 vcc, exec, s[94:95]
	s_cbranch_vccz .LBB0_708

.LBB0_727:
	s_and_b32 s13, s12, 0xff
	s_mov_b64 s[34:35], -1
	s_cmp_lg_u32 s13, 0
	s_mov_b64 s[50:51], -1
	s_nop 0
	s_cbranch_scc0 .LBB0_730
	s_and_b64 vcc, exec, s[50:51]
	s_cbranch_vccz .LBB0_726

.LBB0_744:
	s_and_b32 s13, s12, 0xff
	s_mov_b64 s[30:31], -1
	s_cmp_lg_u32 s13, 0
	s_mov_b64 s[36:37], -1
	s_nop 0
	s_cbranch_scc0 .LBB0_747
	s_and_b64 vcc, exec, s[36:37]
	s_cbranch_vccz .LBB0_743

.LBB0_878:
	global_load_dword v15, v145, s[8:9] sc1
	s_waitcnt lgkmcnt(0)
	global_load_dword v0, v145, s[10:11] sc1
	global_load_dword v1, v145, s[16:17] sc1
	global_load_dword v2, v145, s[28:29] sc1
	global_load_dword v3, v145, s[30:31] sc1
	global_load_dword v4, v145, s[34:35] sc1
	global_load_dword v5, v145, s[36:37] sc1
	global_load_dword v6, v145, s[50:51] sc1
	global_load_dword v7, v145, s[52:53] sc1
	global_load_dword v8, v145, s[54:55] sc1
	global_load_dword v9, v145, s[56:57] sc1
	global_load_dword v10, v145, s[66:67] sc1
	global_load_dword v11, v145, s[70:71] sc1
	global_load_dword v12, v145, s[72:73] sc1
	global_load_dword v13, v145, s[74:75] sc1
	global_load_dword v14, v145, s[82:83] sc1
	s_mov_b64 s[88:89], -1
	s_mov_b64 s[94:95], -1
	s_waitcnt vmcnt(14)
	v_add_u32_e32 v16, v0, v15
	s_waitcnt vmcnt(13)
	v_add_u32_e32 v16, v16, v1
	s_waitcnt vmcnt(12)
	v_add_u32_e32 v16, v16, v2
	s_waitcnt vmcnt(11)
	v_add_u32_e32 v16, v16, v3
	s_waitcnt vmcnt(10)
	v_add_u32_e32 v16, v16, v4
	s_waitcnt vmcnt(9)
	v_add_u32_e32 v16, v16, v5
	s_waitcnt vmcnt(8)
	v_add_u32_e32 v16, v16, v6
	s_waitcnt vmcnt(7)
	v_add_u32_e32 v16, v16, v7
	s_waitcnt vmcnt(6)
	v_add_u32_e32 v16, v16, v8
	s_waitcnt vmcnt(5)
	v_add_u32_e32 v16, v16, v9
	s_waitcnt vmcnt(4)
	v_add_u32_e32 v16, v16, v10
	s_waitcnt vmcnt(3)
	v_add_u32_e32 v16, v16, v11
	s_waitcnt vmcnt(2)
	v_add_u32_e32 v16, v16, v12
	s_waitcnt vmcnt(1)
	v_add_u32_e32 v16, v16, v13
	s_waitcnt vmcnt(0)
	v_add_u32_e32 v16, v16, v14
	v_cmp_eq_u32_e32 vcc, s33, v16
	s_cbranch_vccnz .LBB0_877
	s_and_b32 s14, s13, 0xff
	s_cmp_eq_u32 s14, 0
	s_mov_b64 vcc, -1
	s_nop 0
	s_cbranch_scc1 .LBB0_882
	s_and_b64 vcc, exec, vcc
	s_cbranch_vccz .LBB0_877

.LBB0_896:
	s_and_b32 s13, s12, 0xff
	s_mov_b64 s[36:37], -1
	s_cmp_lg_u32 s13, 0
	s_mov_b64 s[52:53], -1
	s_nop 0
	s_cbranch_scc0 .LBB0_899
	s_and_b64 vcc, exec, s[52:53]
	s_cbranch_vccz .LBB0_895

.LBB0_1094:
	global_load_dword v15, v145, s[10:11] sc1
	s_waitcnt lgkmcnt(0)
	global_load_dword v0, v145, s[16:17] sc1
	global_load_dword v1, v145, s[22:23] sc1
	global_load_dword v2, v145, s[24:25] sc1
	global_load_dword v3, v145, s[26:27] sc1
	global_load_dword v4, v145, s[28:29] sc1
	global_load_dword v5, v145, s[30:31] sc1
	global_load_dword v6, v145, s[34:35] sc1
	global_load_dword v7, v145, s[36:37] sc1
	global_load_dword v8, v145, s[50:51] sc1
	global_load_dword v9, v145, s[52:53] sc1
	global_load_dword v10, v145, s[54:55] sc1
	global_load_dword v11, v145, s[56:57] sc1
	global_load_dword v12, v145, s[66:67] sc1
	global_load_dword v13, v145, s[70:71] sc1
	global_load_dword v14, v145, s[72:73] sc1
	s_mov_b64 s[74:75], -1
	s_mov_b64 s[82:83], -1
	s_waitcnt vmcnt(14)
	v_add_u32_e32 v16, v0, v15
	s_waitcnt vmcnt(13)
	v_add_u32_e32 v16, v16, v1
	s_waitcnt vmcnt(12)
	v_add_u32_e32 v16, v16, v2
	s_waitcnt vmcnt(11)
	v_add_u32_e32 v16, v16, v3
	s_waitcnt vmcnt(10)
	v_add_u32_e32 v16, v16, v4
	s_waitcnt vmcnt(9)
	v_add_u32_e32 v16, v16, v5
	s_waitcnt vmcnt(8)
	v_add_u32_e32 v16, v16, v6
	s_waitcnt vmcnt(7)
	v_add_u32_e32 v16, v16, v7
	s_waitcnt vmcnt(6)
	v_add_u32_e32 v16, v16, v8
	s_waitcnt vmcnt(5)
	v_add_u32_e32 v16, v16, v9
	s_waitcnt vmcnt(4)
	v_add_u32_e32 v16, v16, v10
	s_waitcnt vmcnt(3)
	v_add_u32_e32 v16, v16, v11
	s_waitcnt vmcnt(2)
	v_add_u32_e32 v16, v16, v12
	s_waitcnt vmcnt(1)
	v_add_u32_e32 v16, v16, v13
	s_waitcnt vmcnt(0)
	v_add_u32_e32 v16, v16, v14
	v_cmp_eq_u32_e32 vcc, s33, v16
	s_cbranch_vccnz .LBB0_1093
	s_and_b32 s14, s13, 0xff
	s_cmp_eq_u32 s14, 0
	s_mov_b64 s[88:89], -1
	s_nop 0
	s_cbranch_scc1 .LBB0_1098
	s_and_b64 vcc, exec, s[88:89]
	s_cbranch_vccz .LBB0_1093

.LBB0_1147:
	s_and_b32 s13, s12, 0xff
	s_mov_b64 s[28:29], -1
	s_cmp_lg_u32 s13, 0
	s_mov_b64 s[34:35], -1
	s_nop 0
	s_cbranch_scc0 .LBB0_1150
	s_and_b64 vcc, exec, s[34:35]
	s_cbranch_vccz .LBB0_1146
